# nt on norm-pass streaming row loads; final grid barrier dropped; plus sc1 stores
# speedup vs baseline: 1.0703x; 1.0703x over previous
.LBB0_310:
	s_add_i32 s10, s10, s12
	s_cmp_ge_i32 s10, s9
	s_cselect_b64 s[20:21], -1, 0
	s_and_b64 vcc, exec, s[20:21]
	s_cbranch_vccnz .LBB0_309
	v_lshl_add_u64 v[90:91], s[18:19], 0, v[130:131]
	v_add_co_u32_e32 v78, vcc, 0x2f1e0000, v90
	s_nop 1
	v_addc_co_u32_e32 v79, vcc, 0, v91, vcc
	v_add_co_u32_e32 v92, vcc, 0x29c00000, v90
	s_nop 1
	v_addc_co_u32_e32 v93, vcc, 0, v91, vcc
	global_load_dwordx4 v[66:69], v[78:79], off offset:1024 nt
	global_load_dwordx4 v[70:73], v[78:79], off offset:2048 nt
	global_load_dwordx4 v[74:77], v[92:93], off nt
	s_nop 0
	global_load_dwordx4 v[78:81], v[78:79], off offset:3072 nt
	s_nop 0
	global_load_dwordx4 v[82:85], v[92:93], off offset:1024 nt
	global_load_dwordx4 v[86:89], v[92:93], off offset:2048 nt
	v_add_co_u32_e32 v90, vcc, 0x2f1e1000, v90
	s_nop 1
	v_addc_co_u32_e32 v91, vcc, 0, v91, vcc
	global_load_dwordx4 v[94:97], v[90:91], off nt
	s_nop 0
	global_load_dwordx4 v[90:93], v[92:93], off offset:3072 nt
	s_branch .LBB0_309

.LBB0_639:
	s_add_i32 s14, s14, s16
	s_cmp_ge_i32 s14, s13
	s_cselect_b64 s[24:25], -1, 0
	s_and_b64 vcc, exec, s[24:25]
	s_cbranch_vccnz .LBB0_641
	v_lshl_add_u64 v[90:91], s[94:95], 0, v[134:135]
	v_add_co_u32_e32 v78, vcc, 0x2f1e0000, v90
	s_nop 1
	v_addc_co_u32_e32 v79, vcc, 0, v91, vcc
	v_add_co_u32_e32 v92, vcc, 0x29c00000, v90
	s_nop 1
	v_addc_co_u32_e32 v93, vcc, 0, v91, vcc
	global_load_dwordx4 v[66:69], v[78:79], off offset:1024 nt
	global_load_dwordx4 v[70:73], v[78:79], off offset:2048 nt
	global_load_dwordx4 v[74:77], v[92:93], off nt
	s_nop 0
	global_load_dwordx4 v[78:81], v[78:79], off offset:3072 nt
	s_nop 0
	global_load_dwordx4 v[82:85], v[92:93], off offset:1024 nt
	global_load_dwordx4 v[86:89], v[92:93], off offset:2048 nt
	v_add_co_u32_e32 v90, vcc, 0x2f1e1000, v90
	s_nop 1
	v_addc_co_u32_e32 v91, vcc, 0, v91, vcc
	global_load_dwordx4 v[94:97], v[90:91], off nt
	s_nop 0
	global_load_dwordx4 v[90:93], v[92:93], off offset:3072 nt

.LBB0_1497:
	s_add_i32 s14, s14, s16
	s_cmp_ge_i32 s14, s13
	s_cselect_b64 s[26:27], -1, 0
	s_and_b64 vcc, exec, s[26:27]
	s_cbranch_vccnz .LBB0_1499
	v_lshl_add_u64 v[90:91], s[94:95], 0, v[134:135]
	v_add_co_u32_e32 v78, vcc, 0x2f1e0000, v90
	s_nop 1
	v_addc_co_u32_e32 v79, vcc, 0, v91, vcc
	v_add_co_u32_e32 v92, vcc, 0x29c00000, v90
	s_nop 1
	v_addc_co_u32_e32 v93, vcc, 0, v91, vcc
	global_load_dwordx4 v[66:69], v[78:79], off offset:1024 nt
	global_load_dwordx4 v[70:73], v[78:79], off offset:2048 nt
	global_load_dwordx4 v[74:77], v[92:93], off nt
	s_nop 0
	global_load_dwordx4 v[78:81], v[78:79], off offset:3072 nt
	s_nop 0
	global_load_dwordx4 v[82:85], v[92:93], off offset:1024 nt
	global_load_dwordx4 v[86:89], v[92:93], off offset:2048 nt
	v_add_co_u32_e32 v90, vcc, 0x2f1e1000, v90
	s_nop 1
	v_addc_co_u32_e32 v91, vcc, 0, v91, vcc
	global_load_dwordx4 v[94:97], v[90:91], off nt
	s_nop 0
	global_load_dwordx4 v[90:93], v[92:93], off offset:3072 nt

.LBB0_2039:
	s_add_i32 s10, s10, s12
	s_cmp_ge_i32 s10, s9
	s_cselect_b64 s[22:23], -1, 0
	s_and_b64 vcc, exec, s[22:23]
	s_cbranch_vccnz .LBB0_2038
	v_lshl_add_u64 v[90:91], s[20:21], 0, v[130:131]
	v_add_co_u32_e32 v78, vcc, 0x2f1e0000, v90
	s_nop 1
	v_addc_co_u32_e32 v79, vcc, 0, v91, vcc
	v_add_co_u32_e32 v92, vcc, 0x29c00000, v90
	s_nop 1
	v_addc_co_u32_e32 v93, vcc, 0, v91, vcc
	global_load_dwordx4 v[66:69], v[78:79], off offset:1024 nt
	global_load_dwordx4 v[70:73], v[78:79], off offset:2048 nt
	global_load_dwordx4 v[74:77], v[92:93], off nt
	s_nop 0
	global_load_dwordx4 v[78:81], v[78:79], off offset:3072 nt
	s_nop 0
	global_load_dwordx4 v[82:85], v[92:93], off offset:1024 nt
	global_load_dwordx4 v[86:89], v[92:93], off offset:2048 nt
	v_add_co_u32_e32 v90, vcc, 0x2f1e1000, v90
	s_nop 1
	v_addc_co_u32_e32 v91, vcc, 0, v91, vcc
	global_load_dwordx4 v[94:97], v[90:91], off nt
	s_nop 0
	global_load_dwordx4 v[90:93], v[92:93], off offset:3072 nt
	s_branch .LBB0_2038

.LBB0_2372:
	s_add_i32 s12, s12, s14
	s_cmp_ge_i32 s12, s11
	s_cselect_b64 s[24:25], -1, 0
	s_and_b64 vcc, exec, s[24:25]
	s_cbranch_vccnz .LBB0_2374
	v_lshl_add_u64 v[90:91], s[94:95], 0, v[134:135]
	v_add_co_u32_e32 v78, vcc, 0x2f1e0000, v90
	s_nop 1
	v_addc_co_u32_e32 v79, vcc, 0, v91, vcc
	v_add_co_u32_e32 v92, vcc, 0x29c00000, v90
	s_nop 1
	v_addc_co_u32_e32 v93, vcc, 0, v91, vcc
	global_load_dwordx4 v[66:69], v[78:79], off offset:1024 nt
	global_load_dwordx4 v[70:73], v[78:79], off offset:2048 nt
	global_load_dwordx4 v[74:77], v[92:93], off nt
	s_nop 0
	global_load_dwordx4 v[78:81], v[78:79], off offset:3072 nt
	s_nop 0
	global_load_dwordx4 v[82:85], v[92:93], off offset:1024 nt
	global_load_dwordx4 v[86:89], v[92:93], off offset:2048 nt
	v_add_co_u32_e32 v90, vcc, 0x2f1e1000, v90
	s_nop 1
	v_addc_co_u32_e32 v91, vcc, 0, v91, vcc
	global_load_dwordx4 v[94:97], v[90:91], off nt
	s_nop 0
	global_load_dwordx4 v[90:93], v[92:93], off offset:3072 nt

.LBB0_2914:
	s_add_i32 s8, s8, s10
	s_cmp_ge_i32 s8, s7
	s_cselect_b64 s[20:21], -1, 0
	s_and_b64 vcc, exec, s[20:21]
	s_cbranch_vccnz .LBB0_2913
	v_lshl_add_u64 v[90:91], s[16:17], 0, v[130:131]
	v_add_co_u32_e32 v78, vcc, 0x2f1e0000, v90
	s_nop 1
	v_addc_co_u32_e32 v79, vcc, 0, v91, vcc
	v_add_co_u32_e32 v92, vcc, 0x29c00000, v90
	s_nop 1
	v_addc_co_u32_e32 v93, vcc, 0, v91, vcc
	global_load_dwordx4 v[66:69], v[78:79], off offset:1024 nt
	global_load_dwordx4 v[70:73], v[78:79], off offset:2048 nt
	global_load_dwordx4 v[74:77], v[92:93], off nt
	s_nop 0
	global_load_dwordx4 v[78:81], v[78:79], off offset:3072 nt
	s_nop 0
	global_load_dwordx4 v[82:85], v[92:93], off offset:1024 nt
	global_load_dwordx4 v[86:89], v[92:93], off offset:2048 nt
	v_add_co_u32_e32 v90, vcc, 0x2f1e1000, v90
	s_nop 1
	v_addc_co_u32_e32 v91, vcc, 0, v91, vcc
	global_load_dwordx4 v[94:97], v[90:91], off nt
	s_nop 0
	global_load_dwordx4 v[90:93], v[92:93], off offset:3072 nt
	s_branch .LBB0_2913

.LBB0_3289:
	s_add_i32 s12, s12, s14
	s_cmp_ge_i32 s12, s11
	s_cselect_b64 s[22:23], -1, 0
	s_and_b64 vcc, exec, s[22:23]
	s_cbranch_vccnz .LBB0_3291
	v_lshl_add_u64 v[90:91], s[94:95], 0, v[134:135]
	v_add_co_u32_e32 v78, vcc, 0x2f1e0000, v90
	s_nop 1
	v_addc_co_u32_e32 v79, vcc, 0, v91, vcc
	v_add_co_u32_e32 v92, vcc, 0x29c00000, v90
	s_nop 1
	v_addc_co_u32_e32 v93, vcc, 0, v91, vcc
	global_load_dwordx4 v[66:69], v[78:79], off offset:1024 nt
	global_load_dwordx4 v[70:73], v[78:79], off offset:2048 nt
	global_load_dwordx4 v[74:77], v[92:93], off nt
	s_nop 0
	global_load_dwordx4 v[78:81], v[78:79], off offset:3072 nt
	s_nop 0
	global_load_dwordx4 v[82:85], v[92:93], off offset:1024 nt
	global_load_dwordx4 v[86:89], v[92:93], off offset:2048 nt
	v_add_co_u32_e32 v90, vcc, 0x2f1e1000, v90
	s_nop 1
	v_addc_co_u32_e32 v91, vcc, 0, v91, vcc
	global_load_dwordx4 v[94:97], v[90:91], off nt
	s_nop 0
	global_load_dwordx4 v[90:93], v[92:93], off offset:3072 nt

.LBB0_3561:
	s_add_i32 s4, s4, s6
	s_cmp_ge_i32 s4, s3
	s_cselect_b64 s[12:13], -1, 0
	s_and_b64 vcc, exec, s[12:13]
	s_cbranch_vccnz .LBB0_3560
	v_add_co_u32_e32 v104, vcc, 0x55e0000, v98
	s_nop 1
	v_addc_co_u32_e32 v105, vcc, 0, v99, vcc
	v_add_co_u32_e32 v106, vcc, 0x55e1000, v98
	global_load_dwordx4 v[34:37], v[104:105], off offset:1024 nt
	global_load_dwordx4 v[38:41], v[104:105], off offset:2048 nt
	global_load_dwordx4 v[42:45], v[98:99], off nt
	global_load_dwordx4 v[46:49], v[98:99], off offset:1024 nt
	v_addc_co_u32_e32 v107, vcc, 0, v99, vcc
	global_load_dwordx4 v[50:53], v[104:105], off offset:3072 nt
	global_load_dwordx4 v[58:61], v[106:107], off nt
	global_load_dwordx4 v[54:57], v[98:99], off offset:2048 nt
	global_load_dwordx4 v[62:65], v[98:99], off offset:3072 nt
	s_branch .LBB0_3560

.LBB0_3574:
	s_branch .LBB0_3627
	s_waitcnt vmcnt(0)
	s_waitcnt vmcnt(0)
	s_barrier
	s_mov_b64 s[0:1], exec
	v_readlane_b32 s2, v254, 36
	v_readlane_b32 s3, v254, 37
	s_and_b64 s[2:3], s[0:1], s[2:3]
	s_mov_b64 exec, s[2:3]
	s_cbranch_execz .LBB0_3626
	s_add_u32 s2, s94, 0x4200
	s_addc_u32 s3, s95, 0
	s_add_i32 s4, 0, 0x20160
	v_mov_b32_e32 v0, s4
	s_waitcnt vmcnt(0) expcnt(0) lgkmcnt(0)
	ds_read_b32 v2, v0
	s_add_i32 s4, 0, 0x20164
	v_mov_b32_e32 v0, s4
	ds_read_b32 v0, v0
	s_waitcnt lgkmcnt(1)
	v_cmp_ne_u32_e32 vcc, 0, v2
	s_cbranch_vccnz .LBB0_3590
	s_add_u32 s4, s94, 0x4400
	s_addc_u32 s5, s95, 0
	s_add_u32 s6, s94, 0x4500
	s_addc_u32 s7, s95, 0
	s_add_u32 s8, s94, 0x4600
	s_addc_u32 s9, s95, 0
	s_add_u32 s10, s94, 0x4700
	s_addc_u32 s11, s95, 0
	s_add_u32 s12, s94, 0x4800
	s_addc_u32 s13, s95, 0
	s_add_u32 s14, s94, 0x4900
	s_addc_u32 s15, s95, 0
	s_add_u32 s16, s94, 0x4a00
	s_addc_u32 s17, s95, 0
	s_add_u32 s18, s94, 0x4b00
	s_addc_u32 s19, s95, 0
	s_add_u32 s20, s94, 0x4c00
	s_addc_u32 s21, s95, 0
	s_add_u32 s22, s94, 0x4d00
	s_addc_u32 s23, s95, 0
	s_add_u32 s24, s94, 0x4e00
	s_addc_u32 s25, s95, 0
	s_add_u32 s26, s94, 0x4f00
	s_addc_u32 s27, s95, 0
	v_readlane_b32 s34, v254, 0
	s_add_u32 s28, s94, 0x5000
	v_readlane_b32 s35, v254, 1
	s_addc_u32 s29, s95, 0
	s_load_dwordx2 s[38:39], s[34:35], 0x4
	s_add_u32 s30, s94, 0x5100
	s_addc_u32 s31, s95, 0
	s_add_u32 s34, s94, 0x5200
	s_addc_u32 s35, s95, 0
	s_add_u32 s36, s94, 0x5300
	s_waitcnt lgkmcnt(0)
	s_mul_i32 s44, s38, s90
	s_addc_u32 s37, s95, 0
	s_mul_i32 s44, s44, s39
	s_mov_b32 s45, 1
	v_mov_b32_e32 v16, 0
	s_branch .LBB0_3578
